# static s_setprio 1 for waves 4-7 during GEMM phases (no per-phase flips)
# baseline (speedup 1.0000x reference)
; __device__ __forceinline__ int tid_l() { int t = threadIdx.x; asm volatile("" : "+v"(t)); return t; }
;   __device__ __forceinline__ const char* aptr(const Unit& u) const { return s.aptr(u); }
;   __device__ __forceinline__ const char* bptr(const Unit& u) const { return s.bptr(u); }
;   __device__ __forceinline__ bool next(int i, Unit& u) const { if (i) return false; u = u0; return true; }
; #define PG8_STAGE(bufoff, gbase, voff) do { _Pragma("unroll") for (int _i = 0; _i < 2; ++_i) \
;     __builtin_amdgcn_global_load_lds((const unsigned*)((const char*)(gbase) + (voff)[_i]), (PG8_LAS unsigned*)(lds + (bufoff) + ldsw + _i * 8192), 16, 0, 0); } while (0)
; #define PG8_BAR __builtin_amdgcn_s_barrier()
;   __device__ __forceinline__ int kt(const Unit& u) const { return ((u.pn & 7) < 4) ? 4 : 16; }
; template <class Epi, class Sched>
; __device__ __forceinline__ void gemm_phase(PG8_LAS unsigned char* lds, const int lda, const int ldb, const Sched& S, const Epi& E) {
;   const int tid = tid_l(), wid = __builtin_amdgcn_readfirstlane(tid >> 6), lane = tid & 63, wr = wid >> 2, wc = wid & 3, fr = lane & 15, fq = lane >> 4;
;   unsigned voffA[2], voffB[2];
; #pragma unroll
;   for (int i = 0; i < 2; ++i) { int R, C; stage_rc(tid * 16 + i * 8192, R, C); voffA[i] = (unsigned)(R * lda + C) * 2u; voffB[i] = (unsigned)(R * ldb + C) * 2u; }
;   const size_t kstep = (size_t)(G_BK * 2);
;   const size_t hstepA = (size_t)G_HALF * lda * 2, hstepB = (size_t)G_HALF * ldb * 2;
;   const unsigned ldsw = (unsigned)wid * 1024u;
;   const int aoff = lds_byte(wr * 64 + fr, fq * 8), boff = lds_byte(wc * 32 + fr, fq * 8);
;     ...
;   Unit cur, nxt; int ui = 0;
;   if (!S.next(0, cur)) return;
;   int nt = S.kt(cur);
;   f32x4 acc[2][2][4][2];
; #pragma unroll
;   for (int a = 0; a < 2; ++a)
; #pragma unroll
;     for (int b = 0; b < 2; ++b)
; #pragma unroll
;       for (int m = 0; m < 4; ++m)
; #pragma unroll
;         for (int n = 0; n < 2; ++n) acc[a][b][m][n] = (f32x4){0.f, 0.f, 0.f, 0.f};
;   bf16x8 At[4][2], B0[2][2], B1[2][2];
;   const char* cA = S.aptr(cur); const char* cB = S.bptr(cur);
;   PG8_STAGE(PG8_SB(0, 0), cB, voffB); PG8_STAGE(PG8_SA(0, 0), cA, voffA); PG8_STAGE(PG8_SB(0, 1), cB + hstepB, voffB); PG8_STAGE(PG8_SA(0, 1), cA + hstepA, voffA);
;   if (wr == 1) PG8_BAR;
.LBB0_323:
	s_or_b64 exec, exec, s[0:1]
	s_mul_i32 s1, s88, 0x2120000
	s_mul_hi_u32 s0, s88, 0x2120000
	s_add_u32 s1, s76, s1
	s_addc_u32 s0, s77, s0
	v_writelane_b32 v255, s1, 29
	s_cmp_lg_u32 s88, 3
	v_writelane_b32 v255, s0, 30
	s_cselect_b64 s[56:57], -1, 0
	s_cmp_eq_u32 s88, 3
	s_mov_b64 s[0:1], -1
	s_waitcnt lgkmcnt(0)
	s_barrier
	s_cbranch_scc0 .LBB0_676
	v_readlane_b32 s0, v254, 16
	v_mov_b32_e32 v9, v176
	v_readlane_b32 s1, v254, 17
	s_andn2_b64 vcc, exec, s[0:1]
	v_readfirstlane_b32 s38, v9
	s_cbranch_vccnz .LBB0_675
	v_lshlrev_b32_e32 v1, 4, v9
	v_add_u32_e32 v2, 0x2000, v1
	v_ashrrev_i32_e32 v3, 31, v2
	v_lshrrev_b32_e32 v3, 22, v3
	v_add_u32_e32 v3, v2, v3
	v_ashrrev_i32_e32 v6, 10, v3
	v_mul_i32_i24_e32 v4, 0x400, v6
	v_sub_u32_e32 v2, v2, v4
	v_lshrrev_b32_e32 v4, 4, v2
	v_bitop3_b32 v2, v4, v2, 32 bitop3:0x6c
	v_ashrrev_i32_e32 v4, 31, v2
	v_lshrrev_b32_e32 v4, 26, v4
	v_add_u32_e32 v4, v2, v4
	v_ashrrev_i32_e32 v7, 6, v4
	v_and_b32_e32 v4, 0xc0, v4
	v_sub_u32_e32 v2, v2, v4
	v_mov_b32_e32 v4, 1
	v_lshlrev_b32_e32 v3, 5, v6
	v_ashrrev_i16_sdwa v2, v4, sext(v2) dst_sel:DWORD dst_unused:UNUSED_PAD src0_sel:DWORD src1_sel:BYTE_0
	v_and_b32_e32 v3, 32, v3
	v_bfe_i32 v8, v2, 0, 16
	v_add_u32_e32 v2, v3, v8
	v_lshlrev_b32_e32 v3, 3, v6
	v_and_b32_e32 v3, 0x1ffff0, v3
	v_add_lshl_u32 v3, v7, v3, 11
	v_lshl_add_u32 v132, v2, 1, v3
	v_bfe_i32 v3, v9, 27, 1
	v_lshrrev_b32_e32 v3, 22, v3
	v_add_u32_e32 v3, v1, v3
	v_and_b32_e32 v3, 0xfffffc00, v3
	v_sub_u32_e32 v1, v1, v3
	v_lshrrev_b32_e32 v3, 4, v1
	v_bitop3_b32 v3, v3, v1, 32 bitop3:0x6c
	v_ashrrev_i32_e32 v1, 31, v1
	v_lshrrev_b32_e32 v1, 26, v1
	v_ashrrev_i32_e32 v2, 31, v9
	v_add_u32_e32 v1, v3, v1
	v_lshrrev_b32_e32 v2, 26, v2
	v_ashrrev_i32_e32 v11, 6, v1
	v_add_u32_e32 v2, v9, v2
	v_mul_i32_i24_e32 v1, 64, v11
	v_ashrrev_i32_e32 v10, 6, v2
	v_sub_u32_e32 v1, v3, v1
	v_lshlrev_b32_e32 v2, 5, v10
	v_ashrrev_i16_sdwa v1, v4, sext(v1) dst_sel:DWORD dst_unused:UNUSED_PAD src0_sel:DWORD src1_sel:BYTE_0
	s_ashr_i32 s2, s38, 6
	v_and_b32_e32 v2, 32, v2
	v_bfe_i32 v12, v1, 0, 16
	s_ashr_i32 s0, s38, 8
	s_lshl_b32 s39, s2, 10
	v_add_u32_e32 v1, v2, v12
	v_lshlrev_b32_e32 v2, 3, v10
	v_readlane_b32 s4, v254, 22
	v_readlane_b32 s1, v255, 29
	v_and_b32_e32 v2, 0x1ffff0, v2
	v_readlane_b32 s5, v254, 23
	s_add_u32 s10, s1, s4
	v_readlane_b32 s1, v255, 30
	v_add_lshl_u32 v2, v11, v2, 11
	s_addc_u32 s11, s1, s5
	s_add_i32 s40, s39, 0
	v_lshl_add_u32 v134, v1, 1, v2
	s_add_i32 m0, s40, 0x10000
	v_readlane_b32 s4, v254, 24
	global_load_lds_dwordx4 v134, s[10:11]
	s_add_i32 m0, s40, 0x12000
	v_readlane_b32 s5, v254, 25
	global_load_lds_dwordx4 v132, s[10:11]
	s_mov_b32 m0, s40
	s_add_i32 s41, s40, 0x2000
	v_mov_b32_e32 v135, v0
	s_nop 0
	global_load_lds_dwordx4 v134, s[4:5]
	s_mov_b32 m0, s41
	v_mov_b32_e32 v133, v0
	global_load_lds_dwordx4 v132, s[4:5]
	s_add_u32 s4, s10, 0x40000
	s_addc_u32 s5, s11, 0
	s_add_i32 m0, s40, 0x14000
	s_add_i32 s42, s40, 0x4000
	global_load_lds_dwordx4 v134, s[4:5]
	s_add_i32 m0, s40, 0x16000
	s_add_i32 s43, s40, 0x6000
	global_load_lds_dwordx4 v132, s[4:5]
	v_readlane_b32 s4, v254, 26
	s_mov_b32 m0, s42
	v_readlane_b32 s5, v254, 27
	v_readlane_b32 s54, v253, 44
	v_lshl_add_u64 v[2:3], s[10:11], 0, v[134:135]
	s_cmp_lg_u32 s0, 1
	v_lshl_add_u64 v[4:5], s[10:11], 0, v[132:133]
	v_readlane_b32 s52, v254, 40
	global_load_lds_dwordx4 v134, s[4:5]
	s_mov_b32 m0, s43
	v_readlane_b32 s55, v253, 45
	global_load_lds_dwordx4 v132, s[4:5]
	s_movk_i32 s53, 0x121
	s_cbranch_scc1 .LBB0_327
	s_setprio 1
	s_barrier

; #define PG8_WAIT_V(n) asm volatile("s_waitcnt vmcnt(" #n ")" ::: "memory")
; #define PG8_BAR __builtin_amdgcn_s_barrier()
; template <class Epi, class Sched>
; __device__ __forceinline__ void gemm_phase(PG8_LAS unsigned char* lds, const int lda, const int ldb, const Sched& S, const Epi& E) {
;     ...
;   PG8_WAIT_V(0);
;   if (wr == 0) PG8_BAR;
;   PG8_BAR;
.LBB0_674:
	s_setprio 0
	v_readlane_b32 s40, v253, 12
	v_readlane_b32 s41, v253, 13
	v_readlane_b32 s44, v253, 16
	v_readlane_b32 s45, v253, 17
	v_readlane_b32 s52, v253, 24
	v_readlane_b32 s53, v253, 25
	v_readlane_b32 s54, v253, 26
	v_readlane_b32 s55, v253, 27
	s_barrier
	v_readlane_b32 s42, v253, 14
	v_readlane_b32 s43, v253, 15
	v_readlane_b32 s46, v253, 18
	v_readlane_b32 s47, v253, 19
	v_readlane_b32 s48, v253, 20
	v_readlane_b32 s49, v253, 21
	v_readlane_b32 s50, v253, 22
	v_readlane_b32 s51, v253, 23

; __device__ __forceinline__ int tid_l() { int t = threadIdx.x; asm volatile("" : "+v"(t)); return t; }
;   __device__ __forceinline__ const char* aptr(const Unit& u) const { return s.aptr(u); }
;   __device__ __forceinline__ const char* bptr(const Unit& u) const { return s.bptr(u); }
;   __device__ __forceinline__ bool next(int i, Unit& u) const { if (i) return false; u = u0; return true; }
; #define PG8_STAGE(bufoff, gbase, voff) do { _Pragma("unroll") for (int _i = 0; _i < 2; ++_i) \
;     __builtin_amdgcn_global_load_lds((const unsigned*)((const char*)(gbase) + (voff)[_i]), (PG8_LAS unsigned*)(lds + (bufoff) + ldsw + _i * 8192), 16, 0, 0); } while (0)
; #define PG8_BAR __builtin_amdgcn_s_barrier()
;   __device__ __forceinline__ int kt(const Unit& u) const { return ((u.pn & 7) < 4) ? 4 : 16; }
; template <class Epi, class Sched>
; __device__ __forceinline__ void gemm_phase(PG8_LAS unsigned char* lds, const int lda, const int ldb, const Sched& S, const Epi& E) {
;   const int tid = tid_l(), wid = __builtin_amdgcn_readfirstlane(tid >> 6), lane = tid & 63, wr = wid >> 2, wc = wid & 3, fr = lane & 15, fq = lane >> 4;
;   unsigned voffA[2], voffB[2];
; #pragma unroll
;   for (int i = 0; i < 2; ++i) { int R, C; stage_rc(tid * 16 + i * 8192, R, C); voffA[i] = (unsigned)(R * lda + C) * 2u; voffB[i] = (unsigned)(R * ldb + C) * 2u; }
;   const size_t kstep = (size_t)(G_BK * 2);
;   const size_t hstepA = (size_t)G_HALF * lda * 2, hstepB = (size_t)G_HALF * ldb * 2;
;   const unsigned ldsw = (unsigned)wid * 1024u;
;   const int aoff = lds_byte(wr * 64 + fr, fq * 8), boff = lds_byte(wc * 32 + fr, fq * 8);
;     ...
;   Unit cur, nxt; int ui = 0;
;   if (!S.next(0, cur)) return;
;   int nt = S.kt(cur);
;   f32x4 acc[2][2][4][2];
; #pragma unroll
;   for (int a = 0; a < 2; ++a)
; #pragma unroll
;     for (int b = 0; b < 2; ++b)
; #pragma unroll
;       for (int m = 0; m < 4; ++m)
; #pragma unroll
;         for (int n = 0; n < 2; ++n) acc[a][b][m][n] = (f32x4){0.f, 0.f, 0.f, 0.f};
;   bf16x8 At[4][2], B0[2][2], B1[2][2];
;   const char* cA = S.aptr(cur); const char* cB = S.bptr(cur);
;   PG8_STAGE(PG8_SB(0, 0), cB, voffB); PG8_STAGE(PG8_SA(0, 0), cA, voffA); PG8_STAGE(PG8_SB(0, 1), cB + hstepB, voffB); PG8_STAGE(PG8_SA(0, 1), cA + hstepA, voffA);
;   if (wr == 1) PG8_BAR;
.LBB0_676:
	s_andn2_b64 vcc, exec, s[0:1]
	s_cbranch_vccnz .LBB0_1025
	v_readlane_b32 s0, v253, 51
	v_mov_b32_e32 v9, v176
	v_readlane_b32 s1, v253, 52
	s_andn2_b64 vcc, exec, s[0:1]
	v_readfirstlane_b32 s38, v9
	s_cbranch_vccnz .LBB0_1025
	v_lshlrev_b32_e32 v1, 4, v9
	v_add_u32_e32 v2, 0x2000, v1
	v_ashrrev_i32_e32 v3, 31, v2
	v_lshrrev_b32_e32 v3, 22, v3
	v_add_u32_e32 v3, v2, v3
	v_ashrrev_i32_e32 v6, 10, v3
	v_mul_i32_i24_e32 v4, 0x400, v6
	v_sub_u32_e32 v2, v2, v4
	v_lshrrev_b32_e32 v4, 4, v2
	v_bitop3_b32 v2, v4, v2, 32 bitop3:0x6c
	v_ashrrev_i32_e32 v4, 31, v2
	v_lshrrev_b32_e32 v4, 26, v4
	v_add_u32_e32 v4, v2, v4
	v_ashrrev_i32_e32 v7, 6, v4
	v_and_b32_e32 v4, 0xc0, v4
	v_sub_u32_e32 v2, v2, v4
	v_mov_b32_e32 v4, 1
	v_lshlrev_b32_e32 v3, 5, v6
	v_ashrrev_i16_sdwa v2, v4, sext(v2) dst_sel:DWORD dst_unused:UNUSED_PAD src0_sel:DWORD src1_sel:BYTE_0
	v_and_b32_e32 v3, 32, v3
	v_bfe_i32 v8, v2, 0, 16
	v_add_u32_e32 v2, v3, v8
	v_lshlrev_b32_e32 v3, 3, v6
	v_and_b32_e32 v3, 0x1ffff0, v3
	v_add_lshl_u32 v3, v7, v3, 11
	v_lshl_add_u32 v132, v2, 1, v3
	v_bfe_i32 v3, v9, 27, 1
	v_lshrrev_b32_e32 v3, 22, v3
	v_add_u32_e32 v3, v1, v3
	v_and_b32_e32 v3, 0xfffffc00, v3
	v_sub_u32_e32 v1, v1, v3
	v_lshrrev_b32_e32 v3, 4, v1
	v_bitop3_b32 v3, v3, v1, 32 bitop3:0x6c
	v_ashrrev_i32_e32 v1, 31, v1
	v_lshrrev_b32_e32 v1, 26, v1
	v_ashrrev_i32_e32 v2, 31, v9
	v_add_u32_e32 v1, v3, v1
	v_lshrrev_b32_e32 v2, 26, v2
	v_ashrrev_i32_e32 v11, 6, v1
	v_add_u32_e32 v2, v9, v2
	v_mul_i32_i24_e32 v1, 64, v11
	v_ashrrev_i32_e32 v10, 6, v2
	v_sub_u32_e32 v1, v3, v1
	v_lshlrev_b32_e32 v2, 5, v10
	v_ashrrev_i16_sdwa v1, v4, sext(v1) dst_sel:DWORD dst_unused:UNUSED_PAD src0_sel:DWORD src1_sel:BYTE_0
	s_ashr_i32 s2, s38, 6
	v_and_b32_e32 v2, 32, v2
	v_bfe_i32 v12, v1, 0, 16
	s_ashr_i32 s0, s38, 8
	s_lshl_b32 s39, s2, 10
	v_add_u32_e32 v1, v2, v12
	v_lshlrev_b32_e32 v2, 3, v10
	v_readlane_b32 s4, v254, 28
	v_readlane_b32 s1, v255, 29
	v_and_b32_e32 v2, 0x1ffff0, v2
	v_readlane_b32 s5, v254, 29
	s_add_u32 s12, s1, s4
	v_readlane_b32 s1, v255, 30
	v_add_lshl_u32 v2, v11, v2, 11
	s_addc_u32 s13, s1, s5
	s_add_i32 s40, s39, 0
	v_lshl_add_u32 v134, v1, 1, v2
	s_add_i32 m0, s40, 0x10000
	v_readlane_b32 s4, v254, 32
	global_load_lds_dwordx4 v134, s[12:13]
	s_add_i32 m0, s40, 0x12000
	v_readlane_b32 s5, v254, 33
	global_load_lds_dwordx4 v132, s[12:13]
	s_mov_b32 m0, s40
	s_add_i32 s41, s40, 0x2000
	v_mov_b32_e32 v135, v0
	s_nop 0
	global_load_lds_dwordx4 v134, s[4:5]
	s_mov_b32 m0, s41
	v_mov_b32_e32 v133, v0
	global_load_lds_dwordx4 v132, s[4:5]
	s_add_u32 s4, s12, 0x40000
	s_addc_u32 s5, s13, 0
	s_add_i32 m0, s40, 0x14000
	s_add_i32 s42, s40, 0x4000
	global_load_lds_dwordx4 v134, s[4:5]
	s_add_i32 m0, s40, 0x16000
	s_add_i32 s43, s40, 0x6000
	global_load_lds_dwordx4 v132, s[4:5]
	v_readlane_b32 s4, v254, 34
	s_mov_b32 m0, s42
	v_readlane_b32 s5, v254, 35
	v_readlane_b32 s54, v253, 44
	v_lshl_add_u64 v[2:3], s[12:13], 0, v[134:135]
	s_cmp_lg_u32 s0, 1
	v_lshl_add_u64 v[4:5], s[12:13], 0, v[132:133]
	v_readlane_b32 s52, v254, 40
	global_load_lds_dwordx4 v134, s[4:5]
	s_mov_b32 m0, s43
	v_readlane_b32 s55, v253, 45
	global_load_lds_dwordx4 v132, s[4:5]
	s_movk_i32 s53, 0x145
	s_cbranch_scc1 .LBB0_680
	s_setprio 1
	s_barrier

; #define PG8_WAIT_V(n) asm volatile("s_waitcnt vmcnt(" #n ")" ::: "memory")
; #define PG8_BAR __builtin_amdgcn_s_barrier()
; template <class Epi, class Sched>
; __device__ __forceinline__ void gemm_phase(PG8_LAS unsigned char* lds, const int lda, const int ldb, const Sched& S, const Epi& E) {
;     ...
;   PG8_WAIT_V(0);
;   if (wr == 0) PG8_BAR;
;   PG8_BAR;
.LBB0_1024:
	s_setprio 0
	v_readlane_b32 s40, v253, 12
	v_readlane_b32 s41, v253, 13
	v_readlane_b32 s44, v253, 16
	v_readlane_b32 s45, v253, 17
	v_readlane_b32 s52, v253, 24
	v_readlane_b32 s53, v253, 25
	v_readlane_b32 s54, v253, 26
	v_readlane_b32 s55, v253, 27
	s_movk_i32 s21, 0x210
	s_mov_b32 s26, 0x2aaaaaab
	s_barrier
	v_readlane_b32 s42, v253, 14
	v_readlane_b32 s43, v253, 15
	v_readlane_b32 s46, v253, 18
	v_readlane_b32 s47, v253, 19
	v_readlane_b32 s48, v253, 20
	v_readlane_b32 s49, v253, 21
	v_readlane_b32 s50, v253, 22
	v_readlane_b32 s51, v253, 23

; __device__ __forceinline__ int tid_l() { int t = threadIdx.x; asm volatile("" : "+v"(t)); return t; }
;   __device__ __forceinline__ const char* aptr(const Unit& u) const { return s.aptr(u); }
;   __device__ __forceinline__ const char* bptr(const Unit& u) const { return s.bptr(u); }
;   __device__ __forceinline__ bool next(int i, Unit& u) const { if (i) return false; u = u0; return true; }
; #define PG8_STAGE(bufoff, gbase, voff) do { _Pragma("unroll") for (int _i = 0; _i < 2; ++_i) \
;     __builtin_amdgcn_global_load_lds((const unsigned*)((const char*)(gbase) + (voff)[_i]), (PG8_LAS unsigned*)(lds + (bufoff) + ldsw + _i * 8192), 16, 0, 0); } while (0)
; #define PG8_BAR __builtin_amdgcn_s_barrier()
;   __device__ __forceinline__ int kt(const Unit& u) const { return ((u.pn & 7) < 4) ? 4 : 16; }
; template <class Epi, class Sched>
; __device__ __forceinline__ void gemm_phase(PG8_LAS unsigned char* lds, const int lda, const int ldb, const Sched& S, const Epi& E) {
;   const int tid = tid_l(), wid = __builtin_amdgcn_readfirstlane(tid >> 6), lane = tid & 63, wr = wid >> 2, wc = wid & 3, fr = lane & 15, fq = lane >> 4;
;   unsigned voffA[2], voffB[2];
; #pragma unroll
;   for (int i = 0; i < 2; ++i) { int R, C; stage_rc(tid * 16 + i * 8192, R, C); voffA[i] = (unsigned)(R * lda + C) * 2u; voffB[i] = (unsigned)(R * ldb + C) * 2u; }
;   const size_t kstep = (size_t)(G_BK * 2);
;   const size_t hstepA = (size_t)G_HALF * lda * 2, hstepB = (size_t)G_HALF * ldb * 2;
;   const unsigned ldsw = (unsigned)wid * 1024u;
;   const int aoff = lds_byte(wr * 64 + fr, fq * 8), boff = lds_byte(wc * 32 + fr, fq * 8);
;     ...
;   Unit cur, nxt; int ui = 0;
;   if (!S.next(0, cur)) return;
;   int nt = S.kt(cur);
;   f32x4 acc[2][2][4][2];
; #pragma unroll
;   for (int a = 0; a < 2; ++a)
; #pragma unroll
;     for (int b = 0; b < 2; ++b)
; #pragma unroll
;       for (int m = 0; m < 4; ++m)
; #pragma unroll
;         for (int n = 0; n < 2; ++n) acc[a][b][m][n] = (f32x4){0.f, 0.f, 0.f, 0.f};
;   bf16x8 At[4][2], B0[2][2], B1[2][2];
;   const char* cA = S.aptr(cur); const char* cB = S.bptr(cur);
;   PG8_STAGE(PG8_SB(0, 0), cB, voffB); PG8_STAGE(PG8_SA(0, 0), cA, voffA); PG8_STAGE(PG8_SB(0, 1), cB + hstepB, voffB); PG8_STAGE(PG8_SA(0, 1), cA + hstepA, voffA);
;   if (wr == 1) PG8_BAR;
.LBB0_1077:
	s_or_b64 exec, exec, s[0:1]
	v_readlane_b32 s0, v253, 56
	v_writelane_b32 v255, s56, 31
	v_mov_b32_e32 v1, v176
	v_readlane_b32 s1, v253, 57
	v_writelane_b32 v255, s57, 32
	s_waitcnt lgkmcnt(0)
	s_barrier
	s_andn2_b64 vcc, exec, s[0:1]
	v_readfirstlane_b32 s2, v1
	s_cbranch_vccnz .LBB0_1093
	v_lshlrev_b32_e32 v6, 4, v1
	v_add_u32_e32 v3, 0x2000, v6
	v_ashrrev_i32_e32 v2, 31, v3
	v_lshrrev_b32_e32 v2, 22, v2
	v_add_u32_e32 v2, v3, v2
	v_ashrrev_i32_e32 v2, 10, v2
	v_lshlrev_b32_e32 v4, 5, v2
	v_and_b32_e32 v5, 32, v4
	v_mul_i32_i24_e32 v4, 0x400, v2
	v_sub_u32_e32 v3, v3, v4
	v_lshrrev_b32_e32 v4, 4, v3
	v_bitop3_b32 v4, v4, v3, 32 bitop3:0x6c
	v_ashrrev_i32_e32 v3, 31, v4
	v_lshrrev_b32_e32 v3, 26, v3
	v_add_u32_e32 v7, v4, v3
	v_ashrrev_i32_e32 v3, 6, v7
	v_and_b32_e32 v7, 0xc0, v7
	v_sub_u32_e32 v4, v4, v7
	v_mov_b32_e32 v10, 1
	v_ashrrev_i16_sdwa v4, v10, sext(v4) dst_sel:DWORD dst_unused:UNUSED_PAD src0_sel:DWORD src1_sel:BYTE_0
	v_lshlrev_b32_e32 v7, 3, v2
	v_bfe_i32 v4, v4, 0, 16
	v_and_b32_e32 v7, 0x7fff0, v7
	v_add_u32_e32 v5, v5, v4
	v_add_lshl_u32 v7, v3, v7, 13
	v_lshl_add_u32 v132, v5, 1, v7
	v_ashrrev_i32_e32 v5, 31, v1
	v_lshrrev_b32_e32 v5, 26, v5
	v_add_u32_e32 v5, v1, v5
	v_ashrrev_i32_e32 v5, 6, v5
	v_lshlrev_b32_e32 v7, 5, v5
	v_and_b32_e32 v8, 32, v7
	v_bfe_i32 v7, v1, 27, 1
	v_lshrrev_b32_e32 v7, 22, v7
	v_add_u32_e32 v7, v6, v7
	v_and_b32_e32 v7, 0xfffffc00, v7
	v_sub_u32_e32 v6, v6, v7
	v_lshrrev_b32_e32 v7, 4, v6
	v_bitop3_b32 v7, v7, v6, 32 bitop3:0x6c
	v_ashrrev_i32_e32 v6, 31, v6
	v_lshrrev_b32_e32 v6, 26, v6
	v_add_u32_e32 v6, v7, v6
	v_ashrrev_i32_e32 v6, 6, v6
	v_mul_i32_i24_e32 v9, 64, v6
	v_sub_u32_e32 v7, v7, v9
	s_ashr_i32 s0, s2, 6
	v_ashrrev_i16_sdwa v7, v10, sext(v7) dst_sel:DWORD dst_unused:UNUSED_PAD src0_sel:DWORD src1_sel:BYTE_0
	v_lshlrev_b32_e32 v9, 3, v5
	s_lshl_b32 s20, s0, 10
	v_bfe_i32 v7, v7, 0, 16
	v_and_b32_e32 v9, 0x7fff0, v9
	v_add_u32_e32 v8, v8, v7
	v_add_lshl_u32 v9, v6, v9, 13
	s_add_i32 s21, s20, 0
	v_readlane_b32 s4, v254, 50
	v_lshl_add_u32 v134, v8, 1, v9
	s_add_i32 m0, s21, 0x10000
	v_readlane_b32 s5, v254, 51
	s_add_i32 s22, s21, 0x2000
	s_add_i32 s23, s21, 0x4000
	s_add_i32 s24, s21, 0x6000
	s_ashr_i32 s1, s2, 8
	s_nop 0
	global_load_lds_dwordx4 v134, s[4:5]
	s_add_i32 m0, s21, 0x12000
	s_nop 0
	global_load_lds_dwordx4 v132, s[4:5]
	v_readlane_b32 s4, v254, 46
	s_mov_b32 m0, s21
	v_readlane_b32 s5, v254, 47
	s_nop 4
	global_load_lds_dwordx4 v134, s[4:5]
	s_mov_b32 m0, s22
	s_nop 0
	global_load_lds_dwordx4 v132, s[4:5]
	v_readlane_b32 s4, v254, 44
	s_add_i32 m0, s21, 0x14000
	v_readlane_b32 s5, v254, 45
	s_nop 4
	global_load_lds_dwordx4 v134, s[4:5]
	s_add_i32 m0, s21, 0x16000
	s_cmp_lg_u32 s1, 1
	global_load_lds_dwordx4 v132, s[4:5]
	v_readlane_b32 s4, v254, 48
	s_mov_b32 m0, s23
	v_readlane_b32 s5, v254, 49
	s_nop 4
	global_load_lds_dwordx4 v134, s[4:5]
	s_mov_b32 m0, s24
	s_nop 0
	global_load_lds_dwordx4 v132, s[4:5]
	s_cbranch_scc1 .LBB0_1080
	s_setprio 1
	s_barrier

; #define PG8_WAIT_V(n) asm volatile("s_waitcnt vmcnt(" #n ")" ::: "memory")
; #define PG8_BAR __builtin_amdgcn_s_barrier()
; template <class Epi, class Sched>
; __device__ __forceinline__ void gemm_phase(PG8_LAS unsigned char* lds, const int lda, const int ldb, const Sched& S, const Epi& E) {
;     ...
;   PG8_WAIT_V(0);
;   if (wr == 0) PG8_BAR;
;   PG8_BAR;
.LBB0_1092:
	s_setprio 0
	s_barrier

; template <class Epi, class Sched>
; __device__ __forceinline__ void gemm_phase(PG8_LAS unsigned char* lds, const int lda, const int ldb, const Sched& S, const Epi& E) {
;   const int tid = tid_l(), wid = __builtin_amdgcn_readfirstlane(tid >> 6), lane = tid & 63, wr = wid >> 2, wc = wid & 3, fr = lane & 15, fq = lane >> 4;
;   unsigned voffA[2], voffB[2];
; #pragma unroll
;   for (int i = 0; i < 2; ++i) { int R, C; stage_rc(tid * 16 + i * 8192, R, C); voffA[i] = (unsigned)(R * lda + C) * 2u; voffB[i] = (unsigned)(R * ldb + C) * 2u; }
;   const size_t kstep = (size_t)(G_BK * 2);
;   const size_t hstepA = (size_t)G_HALF * lda * 2, hstepB = (size_t)G_HALF * ldb * 2;
;   const unsigned ldsw = (unsigned)wid * 1024u;
;   const int aoff = lds_byte(wr * 64 + fr, fq * 8), boff = lds_byte(wc * 32 + fr, fq * 8);
;     ...
;   Unit cur, nxt; int ui = 0;
;   if (!S.next(0, cur)) return;
;   int nt = S.kt(cur);
;   f32x4 acc[2][2][4][2];
; #pragma unroll
;   for (int a = 0; a < 2; ++a)
; #pragma unroll
;     for (int b = 0; b < 2; ++b)
; #pragma unroll
;       for (int m = 0; m < 4; ++m)
; #pragma unroll
;         for (int n = 0; n < 2; ++n) acc[a][b][m][n] = (f32x4){0.f, 0.f, 0.f, 0.f};
;   bf16x8 At[4][2], B0[2][2], B1[2][2];
;   __device__ __forceinline__ bool next(int i, Unit& u) const {
;     const int j = i >> 3, s = i & 7;
;     const long L = (long)j * G + c;
;     if (L >= nsuper) return false;
;     int wgid = (int)L;
;     { const int q = nsuper / G_NXCD, r = nsuper % G_NXCD, xcd = wgid % G_NXCD, off = wgid / G_NXCD; wgid = (xcd < r ? xcd * (q + 1) : r * (q + 1) + (xcd - r) * q) + off; }
;     const int nig = G_WGM * 4, gid = wgid / nig, fm = gid * G_WGM, gsz = (nM - fm) < G_WGM ? (nM - fm) : G_WGM;
;     u.pm = fm + ((wgid % nig) % gsz);
;     u.pn = ((wgid % nig) / gsz) * 8 + s;
;     return true;
;   }
;   __device__ __forceinline__ const char* aptr(const Unit& u) const {
;     const int s = u.pn & 7;
;     return (s < 4) ? Y + (size_t)u.pm * (256 * 1024 * 2) + s * 512 : H + (size_t)u.pm * (256 * 1024 * 2);
;   }
;   __device__ __forceinline__ const char* bptr(const Unit& u) const {
;     const int s = u.pn & 7, dq = u.pn >> 3;
;     return (s < 4) ? Wb + (size_t)dq * (256 * 1024 * 2) + s * 512 : Wg + (size_t)(dq * 4 + (s - 4)) * (256 * 1024 * 2);
;   }
;   __device__ __forceinline__ int kt(const Unit& u) const { return ((u.pn & 7) < 4) ? 4 : 16; }
.LBB0_1397:
	s_or_b64 exec, exec, s[0:1]
	s_lshr_b32 s27, s26, 8
	s_lshr_b32 s8, s26, 6
	v_mov_b32_e32 v16, v176
	s_cmp_lt_i32 s68, s8
	s_waitcnt lgkmcnt(0)
	s_barrier
	s_cselect_b64 s[0:1], -1, 0
	s_cmp_ge_i32 s68, s8
	v_readfirstlane_b32 s24, v16
	s_cbranch_scc1 .LBB0_1422
	v_lshlrev_b32_e32 v1, 4, v16
	v_add_u32_e32 v2, 0x2000, v1
	v_ashrrev_i32_e32 v3, 31, v2
	v_lshrrev_b32_e32 v3, 22, v3
	v_add_u32_e32 v3, v2, v3
	v_ashrrev_i32_e32 v10, 10, v3
	v_mul_i32_i24_e32 v4, 0x400, v10
	v_sub_u32_e32 v2, v2, v4
	v_lshrrev_b32_e32 v4, 4, v2
	v_bitop3_b32 v2, v4, v2, 32 bitop3:0x6c
	v_ashrrev_i32_e32 v4, 31, v2
	v_lshrrev_b32_e32 v4, 26, v4
	v_add_u32_e32 v4, v2, v4
	v_ashrrev_i32_e32 v11, 6, v4
	v_and_b32_e32 v4, 0xc0, v4
	v_sub_u32_e32 v2, v2, v4
	v_mov_b32_e32 v4, 1
	v_lshlrev_b32_e32 v3, 5, v10
	v_ashrrev_i16_sdwa v2, v4, sext(v2) dst_sel:DWORD dst_unused:UNUSED_PAD src0_sel:DWORD src1_sel:BYTE_0
	v_and_b32_e32 v3, 32, v3
	v_bfe_i32 v12, v2, 0, 16
	v_add_u32_e32 v2, v3, v12
	v_lshlrev_b32_e32 v3, 3, v10
	v_and_b32_e32 v3, 0x1ffff0, v3
	v_add_lshl_u32 v3, v11, v3, 11
	v_lshl_add_u32 v132, v2, 1, v3
	v_bfe_i32 v3, v16, 27, 1
	v_readlane_b32 s2, v255, 29
	v_lshrrev_b32_e32 v3, 22, v3
	s_add_u32 s25, s2, 0xc80000
	v_readlane_b32 s2, v255, 30
	v_add_u32_e32 v3, v1, v3
	s_addc_u32 s28, s2, 0
	s_ashr_i32 s5, s24, 6
	v_and_b32_e32 v3, 0xfffffc00, v3
	s_lshr_b32 s30, s26, 9
	v_readlane_b32 s6, v253, 48
	s_ashr_i32 s4, s24, 8
	s_lshl_b32 s29, s5, 10
	v_sub_u32_e32 v1, v1, v3
	s_or_b32 s31, s30, 1
	v_readlane_b32 s7, v253, 49
	v_lshrrev_b32_e32 v3, 4, v1
	s_and_b64 s[6:7], s[6:7], exec
	v_bitop3_b32 v3, v3, v1, 32 bitop3:0x6c
	v_ashrrev_i32_e32 v1, 31, v1
	s_cselect_b32 s2, s31, s30
	v_readlane_b32 s6, v253, 50
	v_lshrrev_b32_e32 v1, 26, v1
	s_mul_i32 s2, s2, s6
	v_readlane_b32 s6, v254, 36
	v_ashrrev_i32_e32 v2, 31, v16
	v_add_u32_e32 v1, v3, v1
	s_add_i32 s2, s2, s6
	v_lshrrev_b32_e32 v2, 26, v2
	v_ashrrev_i32_e32 v14, 6, v1
	s_ashr_i32 s6, s2, 31
	v_add_u32_e32 v2, v16, v2
	v_mul_i32_i24_e32 v1, 64, v14
	s_lshr_b32 s6, s6, 27
	v_ashrrev_i32_e32 v13, 6, v2
	v_sub_u32_e32 v1, v3, v1
	s_add_i32 s6, s2, s6
	v_lshlrev_b32_e32 v2, 5, v13
	v_ashrrev_i16_sdwa v1, v4, sext(v1) dst_sel:DWORD dst_unused:UNUSED_PAD src0_sel:DWORD src1_sel:BYTE_0
	s_ashr_i32 s7, s6, 5
	v_and_b32_e32 v2, 32, v2
	v_bfe_i32 v15, v1, 0, 16
	s_lshl_b32 s9, s7, 3
	v_add_u32_e32 v1, v2, v15
	v_lshlrev_b32_e32 v2, 3, v13
	s_sub_i32 s7, s27, s9
	v_and_b32_e32 v2, 0x1ffff0, v2
	s_min_i32 s10, s7, 8
	v_add_lshl_u32 v2, v14, v2, 11
	s_sext_i32_i16 s7, s10
	v_lshl_add_u32 v134, v1, 1, v2
	v_cvt_f32_i32_e32 v1, s7
	s_andn2_b32 s6, s6, 31
	s_sub_i32 s11, s2, s6
	v_cvt_f32_i32_e32 v2, s11
	v_rcp_iflag_f32_e32 v3, v1
	s_xor_b32 s2, s11, s7
	s_ashr_i32 s2, s2, 30
	s_or_b32 s2, s2, 1
	v_mul_f32_e32 v3, v2, v3
	v_trunc_f32_e32 v3, v3
	v_fma_f32 v2, -v3, v1, v2
	v_cvt_i32_f32_e32 v3, v3
	v_cmp_ge_f32_e64 s[6:7], |v2|, |v1|
	s_and_b64 s[6:7], s[6:7], exec
	s_cselect_b32 s2, s2, 0
	v_readfirstlane_b32 s6, v3
	s_add_i32 s2, s6, s2
	s_mul_i32 s6, s2, s10
	s_sub_i32 s6, s11, s6
	s_sext_i32_i16 s6, s6
	s_add_i32 s16, s9, s6
	s_ashr_i32 s17, s16, 31
	s_lshl_b64 s[6:7], s[16:17], 19
	v_readlane_b32 s10, v253, 54
	v_readlane_b32 s11, v253, 55
	s_add_u32 s14, s10, s6
	s_addc_u32 s15, s11, s7
	s_bfe_i64 s[6:7], s[2:3], 0x100000
	s_lshl_b64 s[6:7], s[6:7], 19
	s_add_u32 s18, s25, s6
	s_addc_u32 s19, s28, s7
	s_add_i32 s17, s29, 0
	s_add_i32 m0, s17, 0x10000
	s_add_i32 s34, s17, 0x2000
	global_load_lds_dwordx4 v134, s[18:19]
	s_add_i32 m0, s17, 0x12000
	s_add_u32 s6, s18, 0x40000
	global_load_lds_dwordx4 v132, s[18:19]
	s_mov_b32 m0, s17
	s_addc_u32 s7, s19, 0
	global_load_lds_dwordx4 v134, s[14:15]
	s_mov_b32 m0, s34
	v_mov_b32_e32 v135, v0
	global_load_lds_dwordx4 v132, s[14:15]
	s_add_i32 m0, s17, 0x14000
	v_mov_b32_e32 v133, v0
	global_load_lds_dwordx4 v134, s[6:7]
	s_add_i32 m0, s17, 0x16000
	v_lshl_add_u64 v[8:9], s[18:19], 0, v[134:135]
	global_load_lds_dwordx4 v132, s[6:7]
	s_add_u32 s6, s14, 0x40000
	s_addc_u32 s7, s15, 0
	s_add_i32 s35, s17, 0x4000
	s_mov_b32 m0, s35
	s_add_i32 s36, s17, 0x6000
	global_load_lds_dwordx4 v134, s[6:7]
	s_mov_b32 m0, s36
	v_lshl_add_u64 v[6:7], s[18:19], 0, v[132:133]
	global_load_lds_dwordx4 v132, s[6:7]
	v_lshl_add_u64 v[4:5], s[14:15], 0, v[134:135]
	s_cmp_lg_u32 s4, 1
	v_lshl_add_u64 v[2:3], s[14:15], 0, v[132:133]
	s_cbranch_scc1 .LBB0_1400
	s_setprio 1
	s_barrier

; __device__ __forceinline__ int tid_l() { int t = threadIdx.x; asm volatile("" : "+v"(t)); return t; }
; #define PG8_LAS __attribute__((address_space(3)))
;   __device__ __forceinline__ const char* aptr(const Unit& u) const { return s.aptr(u); }
; template <class Epi, class Sched>
; __device__ __forceinline__ void gemm_phase(PG8_LAS unsigned char* lds, const int lda, const int ldb, const Sched& S, const Epi& E) {
;   const int tid = tid_l(), wid = __builtin_amdgcn_readfirstlane(tid >> 6), lane = tid & 63, wr = wid >> 2, wc = wid & 3, fr = lane & 15, fq = lane >> 4;
;   unsigned voffA[2], voffB[2];
; #pragma unroll
;   for (int i = 0; i < 2; ++i) { int R, C; stage_rc(tid * 16 + i * 8192, R, C); voffA[i] = (unsigned)(R * lda + C) * 2u; voffB[i] = (unsigned)(R * ldb + C) * 2u; }
;   const size_t kstep = (size_t)(G_BK * 2);
;   const size_t hstepA = (size_t)G_HALF * lda * 2, hstepB = (size_t)G_HALF * ldb * 2;
;   const unsigned ldsw = (unsigned)wid * 1024u;
;   const int aoff = lds_byte(wr * 64 + fr, fq * 8), boff = lds_byte(wc * 32 + fr, fq * 8);
;     ...
;   Unit cur, nxt; int ui = 0;
;   if (!S.next(0, cur)) return;
;   int nt = S.kt(cur);
;   f32x4 acc[2][2][4][2];
; #pragma unroll
;   for (int a = 0; a < 2; ++a)
; #pragma unroll
;     for (int b = 0; b < 2; ++b)
; #pragma unroll
;       for (int m = 0; m < 4; ++m)
; #pragma unroll
;         for (int n = 0; n < 2; ++n) acc[a][b][m][n] = (f32x4){0.f, 0.f, 0.f, 0.f};
;   bf16x8 At[4][2], B0[2][2], B1[2][2];
;   const char* cA = S.aptr(cur); const char* cB = S.bptr(cur);
;   PG8_STAGE(PG8_SB(0, 0), cB, voffB); PG8_STAGE(PG8_SA(0, 0), cA, voffA); PG8_STAGE(PG8_SB(0, 1), cB + hstepB, voffB); PG8_STAGE(PG8_SA(0, 1), cA + hstepA, voffA);
;   if (wr == 1) PG8_BAR;
; __device__ __forceinline__ void phase_res(const Params& p, int l, int Mrows, const u16* A, int K, const u16* Bt, int gate_off, bool first, char* smem) {
;   EpiRes E;
;   E.xin_l = first ? p.in[0] : p.out;
;   E.xin_c = first ? p.in[2] : reinterpret_cast<const float*>(p.ws + OFF_XC);
;   E.xout_l = p.out;
;   E.xout_c = reinterpret_cast<float*>(p.ws + OFF_XC);
;   E.mod = reinterpret_cast<const float*>(p.ws + OFF_MOD) + (size_t)l * 33 * 6144;
;   E.gate_off = gate_off;
;   SchedStd S;
;   S.init(Mrows / 256, 4, K, A, (size_t)256 * K * 2, Bt, (size_t)256 * K * 2);
;   gemm_phase((PG8_LAS unsigned char*)(smem), K, K, S, E);
.LBB0_1474:
	s_or_b64 exec, exec, s[4:5]
	s_mul_i32 s2, s88, 0x1090000
	s_lshl_b64 s[4:5], s[2:3], 1
	s_add_u32 s28, s76, s4
	v_mov_b32_e32 v18, v176
	v_cndmask_b32_e64 v1, 0, 1, s[0:1]
	s_addc_u32 s29, s77, s5
	s_waitcnt lgkmcnt(0)
	s_barrier
	v_cmp_ne_u32_e64 s[4:5], 1, v1
	s_andn2_b64 vcc, exec, s[0:1]
	v_readfirstlane_b32 s2, v18
	s_cbranch_vccnz .LBB0_1488
	v_lshlrev_b32_e32 v1, 4, v18
	v_add_u32_e32 v2, 0x2000, v1
	v_ashrrev_i32_e32 v3, 31, v2
	v_lshrrev_b32_e32 v3, 22, v3
	v_add_u32_e32 v3, v2, v3
	v_ashrrev_i32_e32 v10, 10, v3
	v_mul_i32_i24_e32 v3, 0x400, v10
	v_sub_u32_e32 v2, v2, v3
	v_lshrrev_b32_e32 v3, 4, v2
	v_bitop3_b32 v2, v3, v2, 32 bitop3:0x6c
	v_ashrrev_i32_e32 v3, 31, v2
	v_lshrrev_b32_e32 v3, 26, v3
	v_add_u32_e32 v3, v2, v3
	v_ashrrev_i32_e32 v11, 6, v3
	v_lshlrev_b32_e32 v5, 5, v10
	v_and_b32_e32 v3, 0xc0, v3
	v_and_b32_e32 v12, 32, v5
	v_sub_u32_e32 v2, v2, v3
	v_mov_b32_e32 v5, 1
	v_ashrrev_i16_sdwa v2, v5, sext(v2) dst_sel:DWORD dst_unused:UNUSED_PAD src0_sel:DWORD src1_sel:BYTE_0
	v_bfe_i32 v13, v2, 0, 16
	v_bfe_i32 v2, v18, 27, 1
	v_lshrrev_b32_e32 v2, 22, v2
	v_add_u32_e32 v2, v1, v2
	s_add_u32 s30, s28, 0xe80000
	v_and_b32_e32 v2, 0xfffffc00, v2
	s_addc_u32 s31, s29, 0
	s_ashr_i32 s1, s2, 6
	v_sub_u32_e32 v1, v1, v2
	s_lshr_b32 s35, s26, 9
	v_readlane_b32 s10, v253, 48
	s_ashr_i32 s6, s2, 8
	s_lshl_b32 s34, s1, 10
	v_lshrrev_b32_e32 v2, 4, v1
	s_or_b32 s36, s35, 1
	v_readlane_b32 s11, v253, 49
	v_bitop3_b32 v2, v2, v1, 32 bitop3:0x6c
	v_ashrrev_i32_e32 v1, 31, v1
	s_and_b64 s[10:11], s[10:11], exec
	v_lshrrev_b32_e32 v1, 26, v1
	s_cselect_b32 s0, s36, s35
	v_readlane_b32 s7, v253, 50
	v_add_u32_e32 v1, v2, v1
	s_mul_i32 s0, s0, s7
	v_readlane_b32 s7, v254, 36
	v_ashrrev_i32_e32 v14, 6, v1
	v_ashrrev_i32_e32 v1, 31, v18
	s_add_i32 s0, s0, s7
	v_lshrrev_b32_e32 v1, 26, v1
	s_ashr_i32 s7, s0, 31
	v_add_u32_e32 v1, v18, v1
	s_lshr_b32 s7, s7, 27
	v_ashrrev_i32_e32 v15, 6, v1
	s_add_i32 s7, s0, s7
	v_lshlrev_b32_e32 v3, 5, v15
	s_ashr_i32 s9, s7, 5
	v_lshlrev_b32_e32 v1, 3, v15
	v_and_b32_e32 v16, 32, v3
	v_mul_i32_i24_e32 v3, 64, v14
	s_lshl_b32 s9, s9, 3
	v_and_b32_e32 v1, 0x1ffff0, v1
	v_sub_u32_e32 v2, v2, v3
	s_sub_i32 s10, s27, s9
	v_add_u32_e32 v1, v14, v1
	v_ashrrev_i16_sdwa v2, v5, sext(v2) dst_sel:DWORD dst_unused:UNUSED_PAD src0_sel:DWORD src1_sel:BYTE_0
	s_min_i32 s12, s10, 8
	v_lshl_or_b32 v1, v1, 10, v16
	v_bfe_i32 v17, v2, 0, 16
	s_sext_i32_i16 s10, s12
	v_add_lshl_u32 v134, v1, v17, 1
	v_cvt_f32_i32_e32 v1, s10
	s_andn2_b32 s7, s7, 31
	s_sub_i32 s7, s0, s7
	v_cvt_f32_i32_e32 v2, s7
	v_rcp_iflag_f32_e32 v3, v1
	s_xor_b32 s0, s7, s10
	s_ashr_i32 s0, s0, 30
	s_or_b32 s0, s0, 1
	v_mul_f32_e32 v3, v2, v3
	v_trunc_f32_e32 v3, v3
	v_fma_f32 v2, -v3, v1, v2
	v_cvt_i32_f32_e32 v3, v3
	v_cmp_ge_f32_e64 s[10:11], |v2|, |v1|
	s_and_b64 s[10:11], s[10:11], exec
	s_cselect_b32 s0, s0, 0
	v_readfirstlane_b32 s10, v3
	s_add_i32 s0, s10, s0
	s_mul_i32 s10, s0, s12
	s_sub_i32 s7, s7, s10
	s_sext_i32_i16 s7, s7
	s_add_i32 s16, s9, s7
	s_ashr_i32 s17, s16, 31
	s_bfe_i64 s[12:13], s[0:1], 0x100000
	s_lshl_b64 s[10:11], s[16:17], 19
	s_lshl_b64 s[12:13], s[12:13], 19
	v_lshlrev_b32_e32 v4, 3, v10
	s_add_u32 s20, s30, s12
	v_and_b32_e32 v4, 0x1ffff0, v4
	s_addc_u32 s21, s31, s13
	s_add_i32 s17, s34, 0
	v_add_u32_e32 v4, v11, v4
	s_add_i32 m0, s17, 0x10000
	v_lshl_or_b32 v4, v4, 10, v12
	global_load_lds_dwordx4 v134, s[20:21]
	s_add_i32 m0, s17, 0x12000
	v_add_lshl_u32 v132, v4, v13, 1
	s_add_u32 s18, s84, s10
	global_load_lds_dwordx4 v132, s[20:21]
	s_addc_u32 s19, s85, s11
	s_mov_b32 m0, s17
	s_add_i32 s37, s17, 0x2000
	global_load_lds_dwordx4 v134, s[18:19]
	s_mov_b32 m0, s37
	s_add_u32 s10, s20, 0x40000
	global_load_lds_dwordx4 v132, s[18:19]
	s_addc_u32 s11, s21, 0
	s_add_i32 m0, s17, 0x14000
	v_mov_b32_e32 v135, v0
	global_load_lds_dwordx4 v134, s[10:11]
	s_add_i32 m0, s17, 0x16000
	v_mov_b32_e32 v133, v0
	global_load_lds_dwordx4 v132, s[10:11]
	s_add_u32 s10, s18, 0x40000
	s_addc_u32 s11, s19, 0
	s_add_i32 s38, s17, 0x4000
	s_mov_b32 m0, s38
	s_add_i32 s39, s17, 0x6000
	global_load_lds_dwordx4 v134, s[10:11]
	s_mov_b32 m0, s39
	v_lshl_add_u64 v[8:9], s[20:21], 0, v[134:135]
	global_load_lds_dwordx4 v132, s[10:11]
	v_lshl_add_u64 v[6:7], s[20:21], 0, v[132:133]
	v_lshl_add_u64 v[4:5], s[18:19], 0, v[134:135]
	s_cmp_lg_u32 s6, 1
	v_lshl_add_u64 v[2:3], s[18:19], 0, v[132:133]
	s_cbranch_scc1 .LBB0_1477
	s_setprio 1
	s_barrier

; #define PG8_WAIT_V(n) asm volatile("s_waitcnt vmcnt(" #n ")" ::: "memory")
; #define PG8_BAR __builtin_amdgcn_s_barrier()
; template <class Epi, class Sched>
; __device__ __forceinline__ void gemm_phase(PG8_LAS unsigned char* lds, const int lda, const int ldb, const Sched& S, const Epi& E) {
;     ...
;   PG8_WAIT_V(0);
;   if (wr == 0) PG8_BAR;
;   PG8_BAR;
.LBB0_1487:
	s_setprio 0
	v_readlane_b32 s40, v253, 12
	v_readlane_b32 s41, v253, 13
	v_readlane_b32 s44, v253, 16
	v_readlane_b32 s45, v253, 17
	v_readlane_b32 s52, v253, 24
	v_readlane_b32 s53, v253, 25
	v_readlane_b32 s54, v253, 26
	v_readlane_b32 s55, v253, 27
	v_readlane_b32 s38, v255, 23
	s_barrier
	v_readlane_b32 s42, v253, 14
	v_readlane_b32 s43, v253, 15
	v_readlane_b32 s46, v253, 18
	v_readlane_b32 s47, v253, 19
	v_readlane_b32 s48, v253, 20
	v_readlane_b32 s49, v253, 21
	v_readlane_b32 s50, v253, 22
	v_readlane_b32 s51, v253, 23
	v_readlane_b32 s39, v255, 24

; __device__ __forceinline__ int tid_l() { int t = threadIdx.x; asm volatile("" : "+v"(t)); return t; }
; #define PG8_LAS __attribute__((address_space(3)))
;   __device__ __forceinline__ const char* aptr(const Unit& u) const { return s.aptr(u); }
;   __device__ __forceinline__ const char* bptr(const Unit& u) const { return s.bptr(u); }
; #define PG8_BAR __builtin_amdgcn_s_barrier()
; template <class Epi, class Sched>
; __device__ __forceinline__ void gemm_phase(PG8_LAS unsigned char* lds, const int lda, const int ldb, const Sched& S, const Epi& E) {
;   const int tid = tid_l(), wid = __builtin_amdgcn_readfirstlane(tid >> 6), lane = tid & 63, wr = wid >> 2, wc = wid & 3, fr = lane & 15, fq = lane >> 4;
;   unsigned voffA[2], voffB[2];
; #pragma unroll
;   for (int i = 0; i < 2; ++i) { int R, C; stage_rc(tid * 16 + i * 8192, R, C); voffA[i] = (unsigned)(R * lda + C) * 2u; voffB[i] = (unsigned)(R * ldb + C) * 2u; }
;   const size_t kstep = (size_t)(G_BK * 2);
;   const size_t hstepA = (size_t)G_HALF * lda * 2, hstepB = (size_t)G_HALF * ldb * 2;
;   const unsigned ldsw = (unsigned)wid * 1024u;
;   const int aoff = lds_byte(wr * 64 + fr, fq * 8), boff = lds_byte(wc * 32 + fr, fq * 8);
;     ...
;   Unit cur, nxt; int ui = 0;
;   if (!S.next(0, cur)) return;
;   int nt = S.kt(cur);
;   f32x4 acc[2][2][4][2];
; #pragma unroll
;   for (int a = 0; a < 2; ++a)
; #pragma unroll
;     for (int b = 0; b < 2; ++b)
; #pragma unroll
;       for (int m = 0; m < 4; ++m)
; #pragma unroll
;         for (int n = 0; n < 2; ++n) acc[a][b][m][n] = (f32x4){0.f, 0.f, 0.f, 0.f};
;   bf16x8 At[4][2], B0[2][2], B1[2][2];
;   const char* cA = S.aptr(cur); const char* cB = S.bptr(cur);
;   PG8_STAGE(PG8_SB(0, 0), cB, voffB); PG8_STAGE(PG8_SA(0, 0), cA, voffA); PG8_STAGE(PG8_SB(0, 1), cB + hstepB, voffB); PG8_STAGE(PG8_SA(0, 1), cA + hstepA, voffA);
;   if (wr == 1) PG8_BAR;
; __device__ __forceinline__ void phase_ffn1(const Params& p, int l, int Mrows, char* smem) {
;   const u16* H = reinterpret_cast<const u16*>(p.ws + OFF_H);
;   const u16* W1T = reinterpret_cast<const u16*>(p.ws + OFF_W) + (size_t)l * LAYER_W + W1_OFF;
;   EpiFfn1 E;
;   E.HID = reinterpret_cast<u16*>(p.ws + OFF_HID);
;   SchedStd S;
;   S.init(Mrows / 256, 22, 1024, H, (size_t)256 * 1024 * 2, W1T, (size_t)256 * 1024 * 2);
;   gemm_phase((PG8_LAS unsigned char*)(smem), 1024, 1024, S, E);
.LBB0_1597:
	s_or_b64 exec, exec, s[0:1]
	s_mul_i32 s2, s27, 22
	v_mov_b32_e32 v8, v176
	s_waitcnt lgkmcnt(0)
	s_barrier
	s_cmp_ge_i32 s68, s2
	v_readfirstlane_b32 s9, v8
	s_cbranch_scc1 .LBB0_1609
	v_lshlrev_b32_e32 v1, 4, v8
	v_add_u32_e32 v3, 0x2000, v1
	v_ashrrev_i32_e32 v2, 31, v3
	v_lshrrev_b32_e32 v2, 22, v2
	v_add_u32_e32 v2, v3, v2
	v_ashrrev_i32_e32 v2, 10, v2
	v_lshlrev_b32_e32 v4, 5, v2
	v_and_b32_e32 v5, 32, v4
	v_mul_i32_i24_e32 v4, 0x400, v2
	v_sub_u32_e32 v3, v3, v4
	v_lshrrev_b32_e32 v4, 4, v3
	v_bitop3_b32 v4, v4, v3, 32 bitop3:0x6c
	v_ashrrev_i32_e32 v3, 31, v4
	v_lshrrev_b32_e32 v3, 26, v3
	v_add_u32_e32 v6, v4, v3
	v_ashrrev_i32_e32 v3, 6, v6
	v_and_b32_e32 v6, 0xc0, v6
	v_sub_u32_e32 v4, v4, v6
	v_mov_b32_e32 v10, 1
	v_ashrrev_i16_sdwa v4, v10, sext(v4) dst_sel:DWORD dst_unused:UNUSED_PAD src0_sel:DWORD src1_sel:BYTE_0
	v_lshlrev_b32_e32 v6, 3, v2
	v_bfe_i32 v4, v4, 0, 16
	v_and_b32_e32 v6, 0x1ffff0, v6
	v_add_u32_e32 v5, v5, v4
	v_add_lshl_u32 v6, v3, v6, 11
	v_lshl_add_u32 v132, v5, 1, v6
	v_ashrrev_i32_e32 v5, 31, v8
	v_lshrrev_b32_e32 v5, 26, v5
	v_add_u32_e32 v5, v8, v5
	v_ashrrev_i32_e32 v5, 6, v5
	v_lshlrev_b32_e32 v6, 5, v5
	v_and_b32_e32 v9, 32, v6
	v_bfe_i32 v6, v8, 27, 1
	v_lshrrev_b32_e32 v6, 22, v6
	v_readlane_b32 s0, v255, 29
	v_add_u32_e32 v6, v1, v6
	s_add_u32 s24, s0, 0x1080000
	v_readlane_b32 s0, v255, 30
	v_and_b32_e32 v6, 0xfffffc00, v6
	s_addc_u32 s25, s0, 0
	s_ashr_i32 s1, s9, 6
	v_sub_u32_e32 v1, v1, v6
	s_lshr_b32 s31, s2, 3
	v_readlane_b32 s10, v253, 48
	s_ashr_i32 s6, s9, 8
	s_lshl_b32 s30, s1, 10
	v_lshrrev_b32_e32 v6, 4, v1
	s_or_b32 s34, s31, 1
	v_readlane_b32 s11, v253, 49
	v_bitop3_b32 v7, v6, v1, 32 bitop3:0x6c
	v_ashrrev_i32_e32 v1, 31, v1
	s_and_b64 s[10:11], s[10:11], exec
	v_lshrrev_b32_e32 v1, 26, v1
	s_cselect_b32 s0, s34, s31
	v_readlane_b32 s7, v253, 50
	v_add_u32_e32 v1, v7, v1
	s_mul_i32 s0, s0, s7
	v_readlane_b32 s7, v254, 36
	v_ashrrev_i32_e32 v6, 6, v1
	s_add_i32 s0, s0, s7
	v_mul_i32_i24_e32 v1, 64, v6
	s_mul_hi_i32 s7, s0, 0x2e8ba2e9
	v_sub_u32_e32 v1, v7, v1
	s_lshr_b32 s10, s7, 31
	s_ashr_i32 s7, s7, 5
	v_ashrrev_i16_sdwa v1, v10, sext(v1) dst_sel:DWORD dst_unused:UNUSED_PAD src0_sel:DWORD src1_sel:BYTE_0
	s_add_i32 s7, s7, s10
	v_bfe_i32 v7, v1, 0, 16
	s_lshl_b32 s12, s7, 3
	v_add_u32_e32 v1, v9, v7
	v_lshlrev_b32_e32 v9, 3, v5
	s_sub_i32 s10, s27, s12
	v_and_b32_e32 v9, 0x1ffff0, v9
	s_min_i32 s13, s10, 8
	v_add_lshl_u32 v9, v6, v9, 11
	s_sext_i32_i16 s10, s13
	v_lshl_add_u32 v134, v1, 1, v9
	v_cvt_f32_i32_e32 v1, s10
	s_mulk_i32 s7, 0xb0
	s_sub_i32 s7, s0, s7
	v_cvt_f32_i32_e32 v9, s7
	v_rcp_iflag_f32_e32 v10, v1
	s_xor_b32 s0, s7, s10
	s_ashr_i32 s0, s0, 30
	s_or_b32 s0, s0, 1
	v_mul_f32_e32 v10, v9, v10
	v_trunc_f32_e32 v10, v10
	v_fma_f32 v9, -v10, v1, v9
	v_cvt_i32_f32_e32 v10, v10
	v_cmp_ge_f32_e64 s[10:11], |v9|, |v1|
	s_and_b64 s[10:11], s[10:11], exec
	s_cselect_b32 s0, s0, 0
	v_readfirstlane_b32 s10, v10
	s_add_i32 s0, s10, s0
	s_mul_i32 s10, s0, s13
	s_sub_i32 s7, s7, s10
	s_sext_i32_i16 s7, s7
	s_add_i32 s16, s12, s7
	s_ashr_i32 s17, s16, 31
	s_bfe_i64 s[12:13], s[0:1], 0x100000
	s_lshl_b64 s[10:11], s[16:17], 19
	s_lshl_b64 s[12:13], s[12:13], 19
	s_add_u32 s20, s24, s12
	s_addc_u32 s21, s25, s13
	s_add_i32 s17, s30, 0
	s_add_i32 m0, s17, 0x10000
	s_nop 0
	global_load_lds_dwordx4 v134, s[20:21]
	s_add_i32 m0, s17, 0x12000
	s_add_u32 s18, s58, s10
	global_load_lds_dwordx4 v132, s[20:21]
	s_addc_u32 s19, s59, s11
	s_mov_b32 m0, s17
	s_add_i32 s35, s17, 0x2000
	global_load_lds_dwordx4 v134, s[18:19]
	s_mov_b32 m0, s35
	s_add_u32 s10, s20, 0x40000
	global_load_lds_dwordx4 v132, s[18:19]
	s_addc_u32 s11, s21, 0
	s_add_i32 m0, s17, 0x14000
	s_nop 0
	global_load_lds_dwordx4 v134, s[10:11]
	s_add_i32 m0, s17, 0x16000
	s_nop 0
	global_load_lds_dwordx4 v132, s[10:11]
	s_add_u32 s10, s18, 0x40000
	s_addc_u32 s11, s19, 0
	s_add_i32 s36, s17, 0x4000
	s_mov_b32 m0, s36
	s_add_i32 s37, s17, 0x6000
	global_load_lds_dwordx4 v134, s[10:11]
	s_mov_b32 m0, s37
	s_cmp_lg_u32 s6, 1
	global_load_lds_dwordx4 v132, s[10:11]
	s_cbranch_scc1 .LBB0_1600
	s_setprio 1
	s_barrier

; #define PG8_WAIT_V(n) asm volatile("s_waitcnt vmcnt(" #n ")" ::: "memory")
; #define PG8_BAR __builtin_amdgcn_s_barrier()
; template <class Epi, class Sched>
; __device__ __forceinline__ void gemm_phase(PG8_LAS unsigned char* lds, const int lda, const int ldb, const Sched& S, const Epi& E) {
;     ...
;   PG8_WAIT_V(0);
;   if (wr == 0) PG8_BAR;
;   PG8_BAR;
.LBB0_1608:
	s_setprio 0
	s_movk_i32 s24, 0x1000
	s_movk_i32 s25, 0x3000
	s_movk_i32 s30, 0xf000
	s_barrier

; __device__ __forceinline__ int tid_l() { int t = threadIdx.x; asm volatile("" : "+v"(t)); return t; }
; #define PG8_LAS __attribute__((address_space(3)))
;   __device__ __forceinline__ const char* aptr(const Unit& u) const { return s.aptr(u); }
; template <class Epi, class Sched>
; __device__ __forceinline__ void gemm_phase(PG8_LAS unsigned char* lds, const int lda, const int ldb, const Sched& S, const Epi& E) {
;   const int tid = tid_l(), wid = __builtin_amdgcn_readfirstlane(tid >> 6), lane = tid & 63, wr = wid >> 2, wc = wid & 3, fr = lane & 15, fq = lane >> 4;
;   unsigned voffA[2], voffB[2];
; #pragma unroll
;   for (int i = 0; i < 2; ++i) { int R, C; stage_rc(tid * 16 + i * 8192, R, C); voffA[i] = (unsigned)(R * lda + C) * 2u; voffB[i] = (unsigned)(R * ldb + C) * 2u; }
;   const size_t kstep = (size_t)(G_BK * 2);
;   const size_t hstepA = (size_t)G_HALF * lda * 2, hstepB = (size_t)G_HALF * ldb * 2;
;   const unsigned ldsw = (unsigned)wid * 1024u;
;   const int aoff = lds_byte(wr * 64 + fr, fq * 8), boff = lds_byte(wc * 32 + fr, fq * 8);
;     ...
;   Unit cur, nxt; int ui = 0;
;   if (!S.next(0, cur)) return;
;   int nt = S.kt(cur);
;   f32x4 acc[2][2][4][2];
; #pragma unroll
;   for (int a = 0; a < 2; ++a)
; #pragma unroll
;     for (int b = 0; b < 2; ++b)
; #pragma unroll
;       for (int m = 0; m < 4; ++m)
; #pragma unroll
;         for (int n = 0; n < 2; ++n) acc[a][b][m][n] = (f32x4){0.f, 0.f, 0.f, 0.f};
;   bf16x8 At[4][2], B0[2][2], B1[2][2];
;   const char* cA = S.aptr(cur); const char* cB = S.bptr(cur);
;   PG8_STAGE(PG8_SB(0, 0), cB, voffB); PG8_STAGE(PG8_SA(0, 0), cA, voffA); PG8_STAGE(PG8_SB(0, 1), cB + hstepB, voffB); PG8_STAGE(PG8_SA(0, 1), cA + hstepA, voffA);
;   if (wr == 1) PG8_BAR;
; __device__ __forceinline__ void phase_res(const Params& p, int l, int Mrows, const u16* A, int K, const u16* Bt, int gate_off, bool first, char* smem) {
;   EpiRes E;
;   E.xin_l = first ? p.in[0] : p.out;
;   E.xin_c = first ? p.in[2] : reinterpret_cast<const float*>(p.ws + OFF_XC);
;   E.xout_l = p.out;
;   E.xout_c = reinterpret_cast<float*>(p.ws + OFF_XC);
;   E.mod = reinterpret_cast<const float*>(p.ws + OFF_MOD) + (size_t)l * 33 * 6144;
;   E.gate_off = gate_off;
;   SchedStd S;
;   S.init(Mrows / 256, 4, K, A, (size_t)256 * K * 2, Bt, (size_t)256 * K * 2);
;   gemm_phase((PG8_LAS unsigned char*)(smem), K, K, S, E);
.LBB0_1661:
	s_or_b64 exec, exec, s[0:1]
	v_mov_b32_e32 v18, v176
	s_waitcnt lgkmcnt(0)
	s_barrier
	s_and_b64 vcc, exec, s[4:5]
	v_readfirstlane_b32 s2, v18
	s_cbranch_vccnz .LBB0_1679
	v_lshlrev_b32_e32 v1, 4, v18
	v_add_u32_e32 v2, 0x2000, v1
	v_ashrrev_i32_e32 v3, 31, v2
	v_lshrrev_b32_e32 v3, 22, v3
	v_add_u32_e32 v3, v2, v3
	v_ashrrev_i32_e32 v10, 10, v3
	v_mul_i32_i24_e32 v3, 0x400, v10
	v_sub_u32_e32 v2, v2, v3
	v_lshrrev_b32_e32 v3, 4, v2
	v_bitop3_b32 v2, v3, v2, 32 bitop3:0x6c
	v_ashrrev_i32_e32 v3, 31, v2
	v_lshrrev_b32_e32 v3, 26, v3
	v_add_u32_e32 v3, v2, v3
	v_ashrrev_i32_e32 v11, 6, v3
	v_lshlrev_b32_e32 v5, 5, v10
	v_and_b32_e32 v3, 0xc0, v3
	v_and_b32_e32 v12, 32, v5
	v_sub_u32_e32 v2, v2, v3
	v_mov_b32_e32 v5, 1
	v_ashrrev_i16_sdwa v2, v5, sext(v2) dst_sel:DWORD dst_unused:UNUSED_PAD src0_sel:DWORD src1_sel:BYTE_0
	v_bfe_i32 v13, v2, 0, 16
	v_bfe_i32 v2, v18, 27, 1
	v_lshrrev_b32_e32 v2, 22, v2
	v_add_u32_e32 v2, v1, v2
	v_and_b32_e32 v2, 0xfffffc00, v2
	v_sub_u32_e32 v1, v1, v2
	v_lshrrev_b32_e32 v2, 4, v1
	v_bitop3_b32 v2, v2, v1, 32 bitop3:0x6c
	v_ashrrev_i32_e32 v1, 31, v1
	v_lshrrev_b32_e32 v1, 26, v1
	v_add_u32_e32 v1, v2, v1
	v_ashrrev_i32_e32 v14, 6, v1
	v_ashrrev_i32_e32 v1, 31, v18
	v_lshrrev_b32_e32 v1, 26, v1
	v_add_u32_e32 v1, v18, v1
	s_add_u32 s18, s28, 0x1b80000
	v_ashrrev_i32_e32 v15, 6, v1
	s_addc_u32 s19, s29, 0
	s_ashr_i32 s1, s2, 6
	v_lshlrev_b32_e32 v4, 3, v10
	v_lshlrev_b32_e32 v1, 3, v15
	s_lshr_b32 s21, s26, 9
	v_readlane_b32 s6, v253, 48
	s_ashr_i32 s4, s2, 8
	s_lshl_b32 s20, s1, 10
	v_and_b32_e32 v4, 0xfffff0, v4
	v_and_b32_e32 v1, 0xfffff0, v1
	s_or_b32 s22, s21, 1
	v_readlane_b32 s7, v253, 49
	v_add_u32_e32 v4, v11, v4
	s_movk_i32 s0, 0xb00
	v_add_u32_e32 v1, v14, v1
	s_and_b64 s[6:7], s[6:7], exec
	v_mul_lo_u32 v4, v4, s0
	v_mul_lo_u32 v1, v1, s0
	s_cselect_b32 s0, s22, s21
	v_readlane_b32 s5, v253, 50
	s_mul_i32 s0, s0, s5
	v_readlane_b32 s5, v254, 36
	s_add_i32 s0, s0, s5
	s_ashr_i32 s5, s0, 31
	s_lshr_b32 s5, s5, 27
	s_add_i32 s5, s0, s5
	v_lshlrev_b32_e32 v3, 5, v15
	s_ashr_i32 s6, s5, 5
	v_and_b32_e32 v16, 32, v3
	v_mul_i32_i24_e32 v3, 64, v14
	s_lshl_b32 s9, s6, 3
	v_sub_u32_e32 v2, v2, v3
	s_sub_i32 s6, s27, s9
	v_ashrrev_i16_sdwa v2, v5, sext(v2) dst_sel:DWORD dst_unused:UNUSED_PAD src0_sel:DWORD src1_sel:BYTE_0
	s_min_i32 s10, s6, 8
	v_or_b32_e32 v1, v1, v16
	v_bfe_i32 v17, v2, 0, 16
	s_sext_i32_i16 s6, s10
	v_add_lshl_u32 v134, v1, v17, 1
	v_cvt_f32_i32_e32 v1, s6
	s_andn2_b32 s5, s5, 31
	s_sub_i32 s5, s0, s5
	v_cvt_f32_i32_e32 v2, s5
	v_rcp_iflag_f32_e32 v3, v1
	s_xor_b32 s0, s5, s6
	s_ashr_i32 s0, s0, 30
	s_or_b32 s0, s0, 1
	v_mul_f32_e32 v3, v2, v3
	v_trunc_f32_e32 v3, v3
	v_fma_f32 v2, -v3, v1, v2
	v_cvt_i32_f32_e32 v3, v3
	v_cmp_ge_f32_e64 s[6:7], |v2|, |v1|
	s_and_b64 s[6:7], s[6:7], exec
	s_cselect_b32 s0, s0, 0
	v_readfirstlane_b32 s6, v3
	s_add_i32 s0, s6, s0
	s_mul_i32 s6, s0, s10
	s_sub_i32 s5, s5, s6
	s_sext_i32_i16 s5, s5
	s_bfe_i64 s[6:7], s[0:1], 0x100000
	s_add_i32 s37, s9, s5
	s_mul_hi_i32 s7, s6, 0x160000
	s_mul_i32 s6, s6, 0x160000
	s_add_u32 s12, s18, s6
	s_addc_u32 s13, s19, s7
	s_add_i32 s23, s20, 0
	s_add_i32 m0, s23, 0x10000
	v_or_b32_e32 v4, v4, v12
	s_mul_i32 s9, s37, 0x160000
	global_load_lds_dwordx4 v134, s[12:13]
	s_add_i32 m0, s23, 0x12000
	v_add_lshl_u32 v132, v4, v13, 1
	s_mul_hi_i32 s5, s37, 0x160000
	s_add_u32 s10, s84, s9
	global_load_lds_dwordx4 v132, s[12:13]
	s_addc_u32 s11, s85, s5
	s_mov_b32 m0, s23
	s_add_i32 s24, s23, 0x2000
	global_load_lds_dwordx4 v134, s[10:11]
	s_mov_b32 m0, s24
	s_add_u32 s6, s12, 0xb0000
	global_load_lds_dwordx4 v132, s[10:11]
	s_addc_u32 s7, s13, 0
	s_add_i32 m0, s23, 0x14000
	v_mov_b32_e32 v135, v0
	global_load_lds_dwordx4 v134, s[6:7]
	s_add_i32 m0, s23, 0x16000
	v_mov_b32_e32 v133, v0
	global_load_lds_dwordx4 v132, s[6:7]
	s_add_u32 s6, s10, 0xb0000
	s_addc_u32 s7, s11, 0
	s_add_i32 s25, s23, 0x4000
	s_mov_b32 m0, s25
	s_add_i32 s26, s23, 0x6000
	global_load_lds_dwordx4 v134, s[6:7]
	s_mov_b32 m0, s26
	v_lshl_add_u64 v[8:9], s[12:13], 0, v[134:135]
	global_load_lds_dwordx4 v132, s[6:7]
	v_lshl_add_u64 v[6:7], s[12:13], 0, v[132:133]
	v_lshl_add_u64 v[4:5], s[10:11], 0, v[134:135]
	s_cmp_lg_u32 s4, 1
	v_lshl_add_u64 v[2:3], s[10:11], 0, v[132:133]
	s_cbranch_scc1 .LBB0_1664
	s_setprio 1
	s_barrier
